# V s0 reads early with staging writes before MFMA 18 and s_not mask inversions
# speedup vs baseline: 1.0050x; 1.0015x over previous
.Lp1a_end:
	s_waitcnt lgkmcnt(9)
	v_mfma_f32_32x32x16_bf16 v[82:97], v[164:167], v[126:129], v[82:97]
	v_exp_f32_e32 v62, v62
	v_add_f32_e32 v200, v200, v54
	v_exp_f32_e32 v63, v63
	v_add_f32_e32 v201, v201, v55
	v_exp_f32_e32 v64, v64
	s_waitcnt lgkmcnt(8)
	v_mfma_f32_32x32x16_bf16 v[98:113], v[168:171], v[126:129], v[98:113]
	ds_read2_b64 v[164:167], v242 offset0:4 offset1:6
	ds_read2_b64 v[168:171], v163 offset0:36 offset1:38
	v_add_f32_e32 v200, v200, v56
	v_exp_f32_e32 v65, v65
	v_add_f32_e32 v201, v201, v57
	v_cvt_pk_bf16_f32 v228, v58, v59
	v_cvt_pk_bf16_f32 v229, v60, v61
	s_waitcnt lgkmcnt(13)
	v_mfma_f32_32x32x16_bf16 v[18:33], v[238:241], v[224:227], v[18:33]
	v_cvt_pk_bf16_f32 v230, v62, v63
	v_cvt_pk_bf16_f32 v231, v64, v65
	v_exp_f32_e32 v66, v66
	v_add_f32_e32 v200, v200, v58
	v_exp_f32_e32 v67, v67
	v_add_f32_e32 v201, v201, v59
	s_waitcnt lgkmcnt(12)
	v_mfma_f32_32x32x16_bf16 v[34:49], v[234:237], v[224:227], v[34:49]
	v_exp_f32_e32 v68, v68
	v_add_f32_e32 v200, v200, v60
	v_exp_f32_e32 v69, v69
	v_add_f32_e32 v201, v201, v61
	v_exp_f32_e32 v70, v70
	s_waitcnt lgkmcnt(9)
	v_mfma_f32_32x32x16_bf16 v[82:97], v[172:175], v[134:137], v[82:97]
	v_add_f32_e32 v200, v200, v62
	v_exp_f32_e32 v71, v71
	v_add_f32_e32 v201, v201, v63
	v_exp_f32_e32 v72, v72
	v_add_f32_e32 v200, v200, v64
	s_waitcnt lgkmcnt(8)
	v_mfma_f32_32x32x16_bf16 v[98:113], v[176:179], v[134:137], v[98:113]
	ds_read2_b64 v[172:175], v242 offset0:8 offset1:10
	ds_read2_b64 v[176:179], v163 offset0:40 offset1:42
	v_exp_f32_e32 v73, v73
	v_add_f32_e32 v201, v201, v65
	v_cvt_pk_bf16_f32 v224, v66, v67
	v_cvt_pk_bf16_f32 v225, v68, v69
	v_cvt_pk_bf16_f32 v226, v70, v71
	s_waitcnt lgkmcnt(3)
	v_mfma_f32_32x32x16_bf16 v[18:33], v[164:167], v[228:231], v[18:33]
	v_cvt_pk_bf16_f32 v227, v72, v73
	v_exp_f32_e32 v74, v74
	v_add_f32_e32 v200, v200, v66
	v_exp_f32_e32 v75, v75
	v_add_f32_e32 v201, v201, v67
	s_waitcnt lgkmcnt(2)
	v_mfma_f32_32x32x16_bf16 v[34:49], v[168:171], v[228:231], v[34:49]
	v_exp_f32_e32 v76, v76
	v_add_f32_e32 v200, v200, v68
	v_exp_f32_e32 v77, v77
	v_add_f32_e32 v201, v201, v69
	v_exp_f32_e32 v78, v78
	s_waitcnt lgkmcnt(9)
	v_mfma_f32_32x32x16_bf16 v[82:97], v[180:183], v[138:141], v[82:97]
	v_add_f32_e32 v200, v200, v70
	v_exp_f32_e32 v79, v79
	v_add_f32_e32 v201, v201, v71
	v_exp_f32_e32 v80, v80
	v_add_f32_e32 v200, v200, v72
	s_waitcnt lgkmcnt(8)
	v_mfma_f32_32x32x16_bf16 v[98:113], v[184:187], v[138:141], v[98:113]
	ds_read2_b64 v[180:183], v242 offset0:12 offset1:14
	ds_read2_b64 v[184:187], v163 offset0:44 offset1:46
	v_exp_f32_e32 v81, v81
	v_add_f32_e32 v201, v201, v73
	v_cvt_pk_bf16_f32 v228, v74, v75
	v_cvt_pk_bf16_f32 v229, v76, v77
	v_cvt_pk_bf16_f32 v230, v78, v79
	s_waitcnt lgkmcnt(3)
	v_mfma_f32_32x32x16_bf16 v[18:33], v[172:175], v[224:227], v[18:33]
	v_cvt_pk_bf16_f32 v231, v80, v81
	v_add_f32_e32 v200, v200, v74
	v_add_f32_e32 v201, v201, v75
	v_add_f32_e32 v200, v200, v76
	v_add_f32_e32 v201, v201, v77
	v_add_f32_e32 v200, v200, v78
	v_add_f32_e32 v201, v201, v79
	v_add_f32_e32 v200, v200, v80
	s_waitcnt lgkmcnt(2)
	v_mfma_f32_32x32x16_bf16 v[34:49], v[176:179], v[224:227], v[34:49]
	v_add_f32_e32 v201, v201, v81
	v_add_f32_e32 v200, v200, v201
	v_add_f32_e32 v162, v162, v200
	s_waitcnt lgkmcnt(9)
	v_mfma_f32_32x32x16_bf16 v[82:97], v[188:191], v[142:145], v[82:97]
	s_waitcnt lgkmcnt(8)
	v_mfma_f32_32x32x16_bf16 v[98:113], v[192:195], v[142:145], v[98:113]
	s_waitcnt lgkmcnt(7)
	v_mfma_f32_32x32x16_bf16 v[82:97], v[196:199], v[146:149], v[82:97]
	s_waitcnt lgkmcnt(0)
	s_not_b64 s[42:43], s[44:45]
	s_andn2_b64 vcc, exec, s[44:45]
	s_cbranch_vccnz .Lt1a_mid
	s_and_b32 s44, s53, 2
	s_mulk_i32 s44, 0x3400
	s_add_i32 s62, s44, 0
	v_add_u32_e32 v0, s62, v151
	s_waitcnt vmcnt(0)
	ds_write_b128 v0, v[118:121]
	s_and_saveexec_b64 s[44:45], s[40:41]
	v_add_u32_e32 v0, s62, v159
	ds_write_b128 v0, v[6:9]
	s_or_b64 exec, exec, s[44:45]

.Lp2a_end:
	s_waitcnt lgkmcnt(9)
	v_mfma_f32_32x32x16_bf16 v[50:65], v[164:167], v[126:129], v[50:65]
	v_exp_f32_e32 v94, v94
	v_add_f32_e32 v200, v200, v86
	v_exp_f32_e32 v95, v95
	v_add_f32_e32 v201, v201, v87
	v_exp_f32_e32 v96, v96
	s_waitcnt lgkmcnt(8)
	v_mfma_f32_32x32x16_bf16 v[66:81], v[168:171], v[126:129], v[66:81]
	ds_read2_b64 v[164:167], v242 offset0:4 offset1:6
	ds_read2_b64 v[168:171], v163 offset0:36 offset1:38
	v_add_f32_e32 v200, v200, v88
	v_exp_f32_e32 v97, v97
	v_add_f32_e32 v201, v201, v89
	v_cvt_pk_bf16_f32 v228, v90, v91
	v_cvt_pk_bf16_f32 v229, v92, v93
	s_waitcnt lgkmcnt(13)
	v_mfma_f32_32x32x16_bf16 v[18:33], v[238:241], v[224:227], v[18:33]
	v_cvt_pk_bf16_f32 v230, v94, v95
	v_cvt_pk_bf16_f32 v231, v96, v97
	v_exp_f32_e32 v98, v98
	v_add_f32_e32 v200, v200, v90
	v_exp_f32_e32 v99, v99
	v_add_f32_e32 v201, v201, v91
	s_waitcnt lgkmcnt(12)
	v_mfma_f32_32x32x16_bf16 v[34:49], v[234:237], v[224:227], v[34:49]
	v_exp_f32_e32 v100, v100
	v_add_f32_e32 v200, v200, v92
	v_exp_f32_e32 v101, v101
	v_add_f32_e32 v201, v201, v93
	v_exp_f32_e32 v102, v102
	s_waitcnt lgkmcnt(9)
	v_mfma_f32_32x32x16_bf16 v[50:65], v[172:175], v[134:137], v[50:65]
	v_add_f32_e32 v200, v200, v94
	v_exp_f32_e32 v103, v103
	v_add_f32_e32 v201, v201, v95
	v_exp_f32_e32 v104, v104
	v_add_f32_e32 v200, v200, v96
	s_waitcnt lgkmcnt(8)
	v_mfma_f32_32x32x16_bf16 v[66:81], v[176:179], v[134:137], v[66:81]
	ds_read2_b64 v[172:175], v242 offset0:8 offset1:10
	ds_read2_b64 v[176:179], v163 offset0:40 offset1:42
	v_exp_f32_e32 v105, v105
	v_add_f32_e32 v201, v201, v97
	v_cvt_pk_bf16_f32 v224, v98, v99
	v_cvt_pk_bf16_f32 v225, v100, v101
	v_cvt_pk_bf16_f32 v226, v102, v103
	s_waitcnt lgkmcnt(3)
	v_mfma_f32_32x32x16_bf16 v[18:33], v[164:167], v[228:231], v[18:33]
	v_cvt_pk_bf16_f32 v227, v104, v105
	v_exp_f32_e32 v106, v106
	v_add_f32_e32 v200, v200, v98
	v_exp_f32_e32 v107, v107
	v_add_f32_e32 v201, v201, v99
	s_waitcnt lgkmcnt(2)
	v_mfma_f32_32x32x16_bf16 v[34:49], v[168:171], v[228:231], v[34:49]
	v_exp_f32_e32 v108, v108
	v_add_f32_e32 v200, v200, v100
	v_exp_f32_e32 v109, v109
	v_add_f32_e32 v201, v201, v101
	v_exp_f32_e32 v110, v110
	s_waitcnt lgkmcnt(9)
	v_mfma_f32_32x32x16_bf16 v[50:65], v[180:183], v[138:141], v[50:65]
	v_add_f32_e32 v200, v200, v102
	v_exp_f32_e32 v111, v111
	v_add_f32_e32 v201, v201, v103
	v_exp_f32_e32 v112, v112
	v_add_f32_e32 v200, v200, v104
	s_waitcnt lgkmcnt(8)
	v_mfma_f32_32x32x16_bf16 v[66:81], v[184:187], v[138:141], v[66:81]
	ds_read2_b64 v[180:183], v242 offset0:12 offset1:14
	ds_read2_b64 v[184:187], v163 offset0:44 offset1:46
	v_exp_f32_e32 v113, v113
	v_add_f32_e32 v201, v201, v105
	v_cvt_pk_bf16_f32 v228, v106, v107
	v_cvt_pk_bf16_f32 v229, v108, v109
	v_cvt_pk_bf16_f32 v230, v110, v111
	s_waitcnt lgkmcnt(3)
	v_mfma_f32_32x32x16_bf16 v[18:33], v[172:175], v[224:227], v[18:33]
	v_cvt_pk_bf16_f32 v231, v112, v113
	v_add_f32_e32 v200, v200, v106
	v_add_f32_e32 v201, v201, v107
	v_add_f32_e32 v200, v200, v108
	v_add_f32_e32 v201, v201, v109
	v_add_f32_e32 v200, v200, v110
	v_add_f32_e32 v201, v201, v111
	v_add_f32_e32 v200, v200, v112
	s_waitcnt lgkmcnt(2)
	v_mfma_f32_32x32x16_bf16 v[34:49], v[176:179], v[224:227], v[34:49]
	v_add_f32_e32 v201, v201, v113
	v_add_f32_e32 v200, v200, v201
	v_add_f32_e32 v162, v162, v200
	s_waitcnt lgkmcnt(9)
	v_mfma_f32_32x32x16_bf16 v[50:65], v[188:191], v[142:145], v[50:65]
	s_waitcnt lgkmcnt(8)
	v_mfma_f32_32x32x16_bf16 v[66:81], v[192:195], v[142:145], v[66:81]
	s_waitcnt lgkmcnt(7)
	v_mfma_f32_32x32x16_bf16 v[50:65], v[196:199], v[146:149], v[50:65]
	s_waitcnt lgkmcnt(0)
	s_mul_i32 s58, s25, 0x2200
	s_and_b64 vcc, exec, s[44:45]
	s_cbranch_vccnz .Lt2a_mid
	s_and_b32 s44, s60, 3
	s_mulk_i32 s44, 0x3400
	s_add_i32 s52, s44, 0
	v_add_u32_e32 v0, s52, v151
	s_waitcnt vmcnt(0)
	ds_write_b128 v0, v[2:5]
	s_and_saveexec_b64 s[44:45], s[40:41]
	v_add_u32_e32 v0, s52, v159
	ds_write_b128 v0, v[10:13]
	s_or_b64 exec, exec, s[44:45]
